# speedup vs baseline: 1.0275x; 1.0016x over previous
.Lattn_top:
	v_mfma_f32_32x32x16_bf16 v[112:127], v[100:103], v[130:133], 0
	v_add_f32_e32 v100, v82, v80
	v_add_f32_e32 v101, v83, v81
	v_cvt_pk_bf16_f32 v158, v80, v81
	v_cvt_pk_bf16_f32 v159, v82, v83
	v_add_f32_e32 v80, v84, v100
	v_add_f32_e32 v81, v85, v101
	v_add_f32_e32 v146, v86, v80
	v_cvt_pk_bf16_f32 v160, v84, v85
	v_mfma_f32_32x32x16_bf16 v[96:111], v[96:99], v[130:133], 0
	v_add_f32_e32 v84, v87, v81
	v_cvt_pk_bf16_f32 v161, v86, v87
	ds_read_b64_tr_b16 v[80:81], v207 offset:0
	ds_read_b64_tr_b16 v[82:83], v207 offset:512
	v_add_f32_e32 v85, v88, v146
	v_add_f32_e32 v84, v89, v84
	v_mfma_f32_32x32x16_bf16 v[112:127], v[182:185], v[134:137], v[112:127]
	v_add_f32_e32 v146, v90, v85
	v_add_f32_e32 v147, v91, v84
	v_cvt_pk_bf16_f32 v154, v88, v89
	v_cvt_pk_bf16_f32 v155, v90, v91
	ds_read_b64_tr_b16 v[84:85], v207 offset:4096
	ds_read_b64_tr_b16 v[86:87], v207 offset:4608
	v_add_f32_e32 v88, v92, v146
	v_add_f32_e32 v89, v93, v147
	v_mfma_f32_32x32x16_bf16 v[96:111], v[178:181], v[134:137], v[96:111]
	v_add_f32_e32 v146, v94, v88
	v_add_f32_e32 v147, v95, v89
	v_cvt_pk_bf16_f32 v156, v92, v93
	v_cvt_pk_bf16_f32 v157, v94, v95
	ds_read_b64_tr_b16 v[88:89], v207 offset:8192
	ds_read_b64_tr_b16 v[90:91], v207 offset:8704
	v_add_f32_e32 v92, v64, v146
	v_add_f32_e32 v93, v65, v147
	v_mfma_f32_32x32x16_bf16 v[112:127], v[174:177], v[138:141], v[112:127]
	v_add_f32_e32 v92, v66, v92
	v_add_f32_e32 v93, v67, v93
	v_cvt_pk_bf16_f32 v150, v64, v65
	v_cvt_pk_bf16_f32 v151, v66, v67
	ds_read_b64_tr_b16 v[64:65], v207 offset:12288
	ds_read_b64_tr_b16 v[66:67], v207 offset:12800
	v_add_f32_e32 v92, v68, v92
	v_add_f32_e32 v93, v69, v93
	v_mfma_f32_32x32x16_bf16 v[96:111], v[170:173], v[138:141], v[96:111]
	s_add_i32 s90, s33, 4
	s_min_u32 s90, s90, s19
	s_mul_i32 s90, s90, 0x160000
	s_add_i32 m0, s5, 0x4000
	s_add_u32 s100, s44, s90
	s_addc_u32 s101, s45, 0
	global_load_lds_dwordx4 v199, s[100:101]
	v_add_f32_e32 v92, v70, v92
	v_add_f32_e32 v93, v71, v93
	v_cvt_pk_bf16_f32 v152, v68, v69
	v_cvt_pk_bf16_f32 v153, v70, v71
	v_add_f32_e32 v68, v72, v92
	v_add_f32_e32 v69, v73, v93
	v_mfma_f32_32x32x16_bf16 v[112:127], v[166:169], v[142:145], v[112:127]
	s_add_i32 m0, s32, 0x4000
	s_nop 0
	global_load_lds_dwordx4 v199, s[100:101] offset:128
	v_add_f32_e32 v68, v74, v68
	v_add_f32_e32 v69, v75, v69
	v_cvt_pk_bf16_f32 v146, v72, v73
	v_cvt_pk_bf16_f32 v147, v74, v75
	v_add_f32_e32 v68, v76, v68
	v_add_f32_e32 v69, v77, v69
	v_mfma_f32_32x32x16_bf16 v[96:111], v[162:165], v[142:145], v[96:111]
	s_min_u32 s90, s24, s19
	s_mul_i32 s90, s90, 0x160000
	s_add_i32 m0, s22, 0x8000
	s_add_u32 s100, s44, s90
	s_addc_u32 s101, s45, 0
	global_load_lds_dwordx4 v201, s[100:101]
	v_add_f32_e32 v68, v78, v68
	v_add_f32_e32 v69, v79, v69
	v_cvt_pk_bf16_f32 v148, v76, v77
	v_cvt_pk_bf16_f32 v149, v78, v79
	s_nop 0
	v_exp_f32_e32 v112, v112
	v_exp_f32_e32 v113, v113
	s_waitcnt lgkmcnt(4)
	v_mfma_f32_32x32x16_bf16 v[48:63], v[80:83], v[158:161], v[48:63]
	v_add_f32_e32 v92, v68, v69
	ds_read_b64_tr_b16 v[68:69], v207 offset:1024
	ds_read_b64_tr_b16 v[70:71], v207 offset:1536
	v_exp_f32_e32 v114, v114
	v_exp_f32_e32 v115, v115
	v_mfma_f32_32x32x16_bf16 v[32:47], v[84:87], v[158:161], v[32:47]
	ds_read_b64_tr_b16 v[72:73], v207 offset:5120
	ds_read_b64_tr_b16 v[74:75], v207 offset:5632
	v_exp_f32_e32 v116, v116
	v_exp_f32_e32 v117, v117
	s_waitcnt lgkmcnt(4)
	v_mfma_f32_32x32x16_bf16 v[16:31], v[88:91], v[158:161], v[16:31]
	ds_read_b64_tr_b16 v[76:77], v207 offset:9216
	ds_read_b64_tr_b16 v[78:79], v207 offset:9728
	v_exp_f32_e32 v118, v118
	v_exp_f32_e32 v119, v119
	v_mfma_f32_32x32x16_bf16 v[0:15], v[64:67], v[158:161], v[0:15]
	ds_read_b64_tr_b16 v[80:81], v207 offset:13312
	ds_read_b64_tr_b16 v[82:83], v207 offset:13824
	v_exp_f32_e32 v120, v120
	v_exp_f32_e32 v121, v121
	s_waitcnt lgkmcnt(4)
	v_mfma_f32_32x32x16_bf16 v[48:63], v[68:71], v[154:157], v[48:63]
	ds_read_b64_tr_b16 v[84:85], v207 offset:2048
	ds_read_b64_tr_b16 v[86:87], v207 offset:2560
	ds_read_b128 v[68:71], v204 offset:32768
	v_exp_f32_e32 v122, v122
	v_exp_f32_e32 v123, v123
	v_mfma_f32_32x32x16_bf16 v[32:47], v[72:75], v[154:157], v[32:47]
	ds_read_b64_tr_b16 v[72:73], v207 offset:6144
	ds_read_b64_tr_b16 v[74:75], v207 offset:6656
	ds_read_b128 v[64:67], v204 offset:36864
	v_exp_f32_e32 v124, v124
	v_exp_f32_e32 v125, v125
	s_waitcnt lgkmcnt(6)
	v_mfma_f32_32x32x16_bf16 v[16:31], v[76:79], v[154:157], v[16:31]
	ds_read_b64_tr_b16 v[76:77], v207 offset:10240
	ds_read_b64_tr_b16 v[78:79], v207 offset:10752
	ds_read_b128 v[182:185], v128 offset:32768
	v_exp_f32_e32 v126, v126
	v_exp_f32_e32 v127, v127
	v_mfma_f32_32x32x16_bf16 v[0:15], v[80:83], v[154:157], v[0:15]
	ds_read_b64_tr_b16 v[80:81], v207 offset:14336
	ds_read_b64_tr_b16 v[82:83], v207 offset:14848
	ds_read_b128 v[178:181], v128 offset:36864
	v_exp_f32_e32 v96, v96
	v_exp_f32_e32 v97, v97
	s_waitcnt lgkmcnt(7)
	v_mfma_f32_32x32x16_bf16 v[48:63], v[84:87], v[150:153], v[48:63]
	ds_read_b64_tr_b16 v[84:85], v207 offset:3072
	ds_read_b64_tr_b16 v[86:87], v207 offset:3584
	ds_read_b128 v[174:177], v205 offset:32768
	v_exp_f32_e32 v98, v98
	v_exp_f32_e32 v99, v99
	v_mfma_f32_32x32x16_bf16 v[32:47], v[72:75], v[150:153], v[32:47]
	ds_read_b64_tr_b16 v[72:73], v207 offset:7168
	ds_read_b64_tr_b16 v[74:75], v207 offset:7680
	ds_read_b128 v[170:173], v205 offset:36864
	v_exp_f32_e32 v100, v100
	v_exp_f32_e32 v101, v101
	s_waitcnt lgkmcnt(7)
	v_mfma_f32_32x32x16_bf16 v[16:31], v[76:79], v[150:153], v[16:31]
	ds_read_b64_tr_b16 v[76:77], v207 offset:11264
	ds_read_b64_tr_b16 v[78:79], v207 offset:11776
	ds_read_b128 v[166:169], v206 offset:32768
	v_exp_f32_e32 v102, v102
	v_exp_f32_e32 v103, v103
	v_mfma_f32_32x32x16_bf16 v[0:15], v[80:83], v[150:153], v[0:15]
	ds_read_b64_tr_b16 v[80:81], v207 offset:15360
	ds_read_b64_tr_b16 v[82:83], v207 offset:15872
	ds_read_b128 v[162:165], v206 offset:36864
	v_exp_f32_e32 v104, v104
	v_exp_f32_e32 v105, v105
	s_waitcnt lgkmcnt(7)
	v_mfma_f32_32x32x16_bf16 v[48:63], v[84:87], v[146:149], v[48:63]
	s_add_i32 m0, s22, 0x8000
	s_addk_i32 m0, 0x400
	s_add_u32 s100, s100, 0x58000
	s_addc_u32 s101, s101, 0
	global_load_lds_dwordx4 v201, s[100:101]
	v_exp_f32_e32 v106, v106
	v_exp_f32_e32 v107, v107
	v_mfma_f32_32x32x16_bf16 v[32:47], v[72:75], v[146:149], v[32:47]
	v_exp_f32_e32 v108, v108
	v_exp_f32_e32 v109, v109
	s_waitcnt lgkmcnt(1)
	v_mfma_f32_32x32x16_bf16 v[16:31], v[76:79], v[146:149], v[16:31]
	v_exp_f32_e32 v110, v110
	v_exp_f32_e32 v111, v111
	v_mfma_f32_32x32x16_bf16 v[0:15], v[80:83], v[146:149], v[0:15]
	v_add_f32_e32 v186, v209, v92
	s_waitcnt vmcnt(4) lgkmcnt(0)
	s_barrier
	v_mfma_f32_32x32x16_bf16 v[80:95], v[68:71], v[130:133], 0
	v_add_f32_e32 v68, v114, v112
	v_add_f32_e32 v69, v115, v113
	v_cvt_pk_bf16_f32 v158, v112, v113
	v_cvt_pk_bf16_f32 v159, v114, v115
	v_add_f32_e32 v68, v116, v68
	v_add_f32_e32 v112, v117, v69
	v_add_f32_e32 v146, v118, v68
	v_cvt_pk_bf16_f32 v160, v116, v117
	v_mfma_f32_32x32x16_bf16 v[64:79], v[64:67], v[130:133], 0
	v_add_f32_e32 v116, v119, v112
	v_cvt_pk_bf16_f32 v161, v118, v119
	ds_read_b64_tr_b16 v[112:113], v207 offset:16384
	ds_read_b64_tr_b16 v[114:115], v207 offset:16896
	v_add_f32_e32 v117, v120, v146
	v_add_f32_e32 v116, v121, v116
	v_mfma_f32_32x32x16_bf16 v[80:95], v[182:185], v[134:137], v[80:95]
	v_add_f32_e32 v146, v122, v117
	v_add_f32_e32 v147, v123, v116
	v_cvt_pk_bf16_f32 v154, v120, v121
	v_cvt_pk_bf16_f32 v155, v122, v123
	ds_read_b64_tr_b16 v[116:117], v207 offset:20480
	ds_read_b64_tr_b16 v[118:119], v207 offset:20992
	v_add_f32_e32 v120, v124, v146
	v_add_f32_e32 v121, v125, v147
	v_mfma_f32_32x32x16_bf16 v[64:79], v[178:181], v[134:137], v[64:79]
	v_add_f32_e32 v146, v126, v120
	v_add_f32_e32 v147, v127, v121
	v_cvt_pk_bf16_f32 v156, v124, v125
	v_cvt_pk_bf16_f32 v157, v126, v127
	ds_read_b64_tr_b16 v[120:121], v207 offset:24576
	ds_read_b64_tr_b16 v[122:123], v207 offset:25088
	v_add_f32_e32 v124, v96, v146
	v_add_f32_e32 v125, v97, v147
	v_mfma_f32_32x32x16_bf16 v[80:95], v[174:177], v[138:141], v[80:95]
	v_add_f32_e32 v124, v98, v124
	v_add_f32_e32 v125, v99, v125
	v_cvt_pk_bf16_f32 v150, v96, v97
	v_cvt_pk_bf16_f32 v151, v98, v99
	ds_read_b64_tr_b16 v[96:97], v207 offset:28672
	ds_read_b64_tr_b16 v[98:99], v207 offset:29184
	v_add_f32_e32 v124, v100, v124
	v_add_f32_e32 v125, v101, v125
	v_mfma_f32_32x32x16_bf16 v[64:79], v[170:173], v[138:141], v[64:79]
	s_add_i32 s90, s33, 5
	s_min_u32 s90, s90, s19
	s_mul_i32 s90, s90, 0x160000
	s_add_i32 m0, s5, 0x8000
	s_add_u32 s100, s44, s90
	s_addc_u32 s101, s45, 0
	global_load_lds_dwordx4 v199, s[100:101]
	v_add_f32_e32 v124, v102, v124
	v_add_f32_e32 v125, v103, v125
	v_cvt_pk_bf16_f32 v152, v100, v101
	v_cvt_pk_bf16_f32 v153, v102, v103
	v_add_f32_e32 v100, v104, v124
	v_add_f32_e32 v101, v105, v125
	v_mfma_f32_32x32x16_bf16 v[80:95], v[166:169], v[142:145], v[80:95]
	s_add_i32 m0, s32, 0x8000
	s_nop 0
	global_load_lds_dwordx4 v199, s[100:101] offset:128
	v_add_f32_e32 v100, v106, v100
	v_add_f32_e32 v101, v107, v101
	v_cvt_pk_bf16_f32 v146, v104, v105
	v_cvt_pk_bf16_f32 v147, v106, v107
	v_add_f32_e32 v100, v108, v100
	v_add_f32_e32 v101, v109, v101
	v_mfma_f32_32x32x16_bf16 v[64:79], v[162:165], v[142:145], v[64:79]
	s_add_i32 s90, s33, 3
	s_min_u32 s90, s90, s19
	s_mul_i32 s90, s90, 0x160000
	s_add_i32 m0, s22, 0x0
	s_add_u32 s100, s44, s90
	s_addc_u32 s101, s45, 0
	global_load_lds_dwordx4 v201, s[100:101]
	v_add_f32_e32 v100, v110, v100
	v_add_f32_e32 v101, v111, v101
	v_cvt_pk_bf16_f32 v148, v108, v109
	v_cvt_pk_bf16_f32 v149, v110, v111
	v_add_f32_e32 v100, v100, v101
	v_exp_f32_e32 v80, v80
	v_exp_f32_e32 v81, v81
	s_waitcnt lgkmcnt(4)
	v_mfma_f32_32x32x16_bf16 v[48:63], v[112:115], v[158:161], v[48:63]
	v_add_f32_e32 v209, v186, v100
	ds_read_b64_tr_b16 v[100:101], v207 offset:17408
	ds_read_b64_tr_b16 v[102:103], v207 offset:17920
	v_exp_f32_e32 v82, v82
	v_exp_f32_e32 v83, v83
	v_mfma_f32_32x32x16_bf16 v[32:47], v[116:119], v[158:161], v[32:47]
	ds_read_b64_tr_b16 v[104:105], v207 offset:21504
	ds_read_b64_tr_b16 v[106:107], v207 offset:22016
	v_exp_f32_e32 v84, v84
	v_exp_f32_e32 v85, v85
	s_waitcnt lgkmcnt(4)
	v_mfma_f32_32x32x16_bf16 v[16:31], v[120:123], v[158:161], v[16:31]
	ds_read_b64_tr_b16 v[108:109], v207 offset:25600
	ds_read_b64_tr_b16 v[110:111], v207 offset:26112
	v_exp_f32_e32 v86, v86
	v_exp_f32_e32 v87, v87
	v_mfma_f32_32x32x16_bf16 v[0:15], v[96:99], v[158:161], v[0:15]
	ds_read_b64_tr_b16 v[112:113], v207 offset:29696
	ds_read_b64_tr_b16 v[114:115], v207 offset:30208
	v_exp_f32_e32 v88, v88
	v_exp_f32_e32 v89, v89
	s_waitcnt lgkmcnt(4)
	v_mfma_f32_32x32x16_bf16 v[48:63], v[100:103], v[154:157], v[48:63]
	ds_read_b64_tr_b16 v[116:117], v207 offset:18432
	ds_read_b64_tr_b16 v[118:119], v207 offset:18944
	ds_read_b128 v[100:103], v204
	v_exp_f32_e32 v90, v90
	v_exp_f32_e32 v91, v91
	v_mfma_f32_32x32x16_bf16 v[32:47], v[104:107], v[154:157], v[32:47]
	ds_read_b64_tr_b16 v[104:105], v207 offset:22528
	ds_read_b64_tr_b16 v[106:107], v207 offset:23040
	ds_read_b128 v[96:99], v204 offset:4096
	v_exp_f32_e32 v92, v92
	v_exp_f32_e32 v93, v93
	s_waitcnt lgkmcnt(6)
	v_mfma_f32_32x32x16_bf16 v[16:31], v[108:111], v[154:157], v[16:31]
	ds_read_b64_tr_b16 v[108:109], v207 offset:26624
	ds_read_b64_tr_b16 v[110:111], v207 offset:27136
	ds_read_b128 v[182:185], v128
	v_exp_f32_e32 v94, v94
	v_exp_f32_e32 v95, v95
	v_mfma_f32_32x32x16_bf16 v[0:15], v[112:115], v[154:157], v[0:15]
	ds_read_b64_tr_b16 v[112:113], v207 offset:30720
	ds_read_b64_tr_b16 v[114:115], v207 offset:31232
	ds_read_b128 v[178:181], v128 offset:4096
	v_exp_f32_e32 v64, v64
	v_exp_f32_e32 v65, v65
	s_waitcnt lgkmcnt(7)
	v_mfma_f32_32x32x16_bf16 v[48:63], v[116:119], v[150:153], v[48:63]
	ds_read_b64_tr_b16 v[116:117], v207 offset:19456
	ds_read_b64_tr_b16 v[118:119], v207 offset:19968
	ds_read_b128 v[174:177], v205
	v_exp_f32_e32 v66, v66
	v_exp_f32_e32 v67, v67
	v_mfma_f32_32x32x16_bf16 v[32:47], v[104:107], v[150:153], v[32:47]
	ds_read_b64_tr_b16 v[104:105], v207 offset:23552
	ds_read_b64_tr_b16 v[106:107], v207 offset:24064
	ds_read_b128 v[170:173], v205 offset:4096
	v_exp_f32_e32 v68, v68
	v_exp_f32_e32 v69, v69
	s_waitcnt lgkmcnt(7)
	v_mfma_f32_32x32x16_bf16 v[16:31], v[108:111], v[150:153], v[16:31]
	ds_read_b64_tr_b16 v[108:109], v207 offset:27648
	ds_read_b64_tr_b16 v[110:111], v207 offset:28160
	ds_read_b128 v[166:169], v206
	v_exp_f32_e32 v70, v70
	v_exp_f32_e32 v71, v71
	v_mfma_f32_32x32x16_bf16 v[0:15], v[112:115], v[150:153], v[0:15]
	ds_read_b64_tr_b16 v[112:113], v207 offset:31744
	ds_read_b64_tr_b16 v[114:115], v207 offset:32256
	ds_read_b128 v[162:165], v206 offset:4096
	v_exp_f32_e32 v72, v72
	v_exp_f32_e32 v73, v73
	s_waitcnt lgkmcnt(7)
	v_mfma_f32_32x32x16_bf16 v[48:63], v[116:119], v[146:149], v[48:63]
	s_add_i32 m0, s22, 0x0
	s_addk_i32 m0, 0x400
	s_add_u32 s100, s100, 0x58000
	s_addc_u32 s101, s101, 0
	global_load_lds_dwordx4 v201, s[100:101]
	v_exp_f32_e32 v74, v74
	v_exp_f32_e32 v75, v75
	v_mfma_f32_32x32x16_bf16 v[32:47], v[104:107], v[146:149], v[32:47]
	v_exp_f32_e32 v76, v76
	v_exp_f32_e32 v77, v77
	s_waitcnt lgkmcnt(1)
	v_mfma_f32_32x32x16_bf16 v[16:31], v[108:111], v[146:149], v[16:31]
	v_exp_f32_e32 v78, v78
	v_exp_f32_e32 v79, v79
	v_mfma_f32_32x32x16_bf16 v[0:15], v[112:115], v[146:149], v[0:15]
	s_cmp_ge_u32 s24, s4
	s_mov_b32 s33, s24
	s_cbranch_scc1 .Lattn_exit
	s_add_i32 s24, s33, 2
	s_waitcnt vmcnt(4) lgkmcnt(0)
	s_barrier
	v_mfma_f32_32x32x16_bf16 v[112:127], v[100:103], v[130:133], 0
	v_add_f32_e32 v100, v82, v80
	v_add_f32_e32 v101, v83, v81
	v_cvt_pk_bf16_f32 v158, v80, v81
	v_cvt_pk_bf16_f32 v159, v82, v83
	v_add_f32_e32 v80, v84, v100
	v_add_f32_e32 v81, v85, v101
	v_add_f32_e32 v146, v86, v80
	v_cvt_pk_bf16_f32 v160, v84, v85
	v_mfma_f32_32x32x16_bf16 v[96:111], v[96:99], v[130:133], 0
	v_add_f32_e32 v84, v87, v81
	v_cvt_pk_bf16_f32 v161, v86, v87
	ds_read_b64_tr_b16 v[80:81], v207 offset:32768
	ds_read_b64_tr_b16 v[82:83], v207 offset:33280
	v_add_f32_e32 v85, v88, v146
	v_add_f32_e32 v84, v89, v84
	v_mfma_f32_32x32x16_bf16 v[112:127], v[182:185], v[134:137], v[112:127]
	v_add_f32_e32 v146, v90, v85
	v_add_f32_e32 v147, v91, v84
	v_cvt_pk_bf16_f32 v154, v88, v89
	v_cvt_pk_bf16_f32 v155, v90, v91
	ds_read_b64_tr_b16 v[84:85], v207 offset:36864
	ds_read_b64_tr_b16 v[86:87], v207 offset:37376
	v_add_f32_e32 v88, v92, v146
	v_add_f32_e32 v89, v93, v147
	v_mfma_f32_32x32x16_bf16 v[96:111], v[178:181], v[134:137], v[96:111]
	v_add_f32_e32 v146, v94, v88
	v_add_f32_e32 v147, v95, v89
	v_cvt_pk_bf16_f32 v156, v92, v93
	v_cvt_pk_bf16_f32 v157, v94, v95
	ds_read_b64_tr_b16 v[88:89], v207 offset:40960
	ds_read_b64_tr_b16 v[90:91], v207 offset:41472
	v_add_f32_e32 v92, v64, v146
	v_add_f32_e32 v93, v65, v147
	v_mfma_f32_32x32x16_bf16 v[112:127], v[174:177], v[138:141], v[112:127]
	v_add_f32_e32 v92, v66, v92
	v_add_f32_e32 v93, v67, v93
	v_cvt_pk_bf16_f32 v150, v64, v65
	v_cvt_pk_bf16_f32 v151, v66, v67
	ds_read_b64_tr_b16 v[64:65], v207 offset:45056
	ds_read_b64_tr_b16 v[66:67], v207 offset:45568
	v_add_f32_e32 v92, v68, v92
	v_add_f32_e32 v93, v69, v93
	v_mfma_f32_32x32x16_bf16 v[96:111], v[170:173], v[138:141], v[96:111]
	s_add_i32 s90, s33, 4
	s_min_u32 s90, s90, s19
	s_mul_i32 s90, s90, 0x160000
	s_add_i32 m0, s5, 0x0
	s_add_u32 s100, s44, s90
	s_addc_u32 s101, s45, 0
	global_load_lds_dwordx4 v199, s[100:101]
	v_add_f32_e32 v92, v70, v92
	v_add_f32_e32 v93, v71, v93
	v_cvt_pk_bf16_f32 v152, v68, v69
	v_cvt_pk_bf16_f32 v153, v70, v71
	v_add_f32_e32 v68, v72, v92
	v_add_f32_e32 v69, v73, v93
	v_mfma_f32_32x32x16_bf16 v[112:127], v[166:169], v[142:145], v[112:127]
	s_add_i32 m0, s32, 0x0
	s_nop 0
	global_load_lds_dwordx4 v199, s[100:101] offset:128
	v_add_f32_e32 v68, v74, v68
	v_add_f32_e32 v69, v75, v69
	v_cvt_pk_bf16_f32 v146, v72, v73
	v_cvt_pk_bf16_f32 v147, v74, v75
	v_add_f32_e32 v68, v76, v68
	v_add_f32_e32 v69, v77, v69
	v_mfma_f32_32x32x16_bf16 v[96:111], v[162:165], v[142:145], v[96:111]
	s_min_u32 s90, s24, s19
	s_mul_i32 s90, s90, 0x160000
	s_add_i32 m0, s22, 0x4000
	s_add_u32 s100, s44, s90
	s_addc_u32 s101, s45, 0
	global_load_lds_dwordx4 v201, s[100:101]
	v_add_f32_e32 v68, v78, v68
	v_add_f32_e32 v69, v79, v69
	v_cvt_pk_bf16_f32 v148, v76, v77
	v_cvt_pk_bf16_f32 v149, v78, v79
	s_nop 0
	v_exp_f32_e32 v112, v112
	v_exp_f32_e32 v113, v113
	s_waitcnt lgkmcnt(4)
	v_mfma_f32_32x32x16_bf16 v[48:63], v[80:83], v[158:161], v[48:63]
	v_add_f32_e32 v92, v68, v69
	ds_read_b64_tr_b16 v[68:69], v207 offset:33792
	ds_read_b64_tr_b16 v[70:71], v207 offset:34304
	v_exp_f32_e32 v114, v114
	v_exp_f32_e32 v115, v115
	v_mfma_f32_32x32x16_bf16 v[32:47], v[84:87], v[158:161], v[32:47]
	ds_read_b64_tr_b16 v[72:73], v207 offset:37888
	ds_read_b64_tr_b16 v[74:75], v207 offset:38400
	v_exp_f32_e32 v116, v116
	v_exp_f32_e32 v117, v117
	s_waitcnt lgkmcnt(4)
	v_mfma_f32_32x32x16_bf16 v[16:31], v[88:91], v[158:161], v[16:31]
	ds_read_b64_tr_b16 v[76:77], v207 offset:41984
	ds_read_b64_tr_b16 v[78:79], v207 offset:42496
	v_exp_f32_e32 v118, v118
	v_exp_f32_e32 v119, v119
	v_mfma_f32_32x32x16_bf16 v[0:15], v[64:67], v[158:161], v[0:15]
	ds_read_b64_tr_b16 v[80:81], v207 offset:46080
	ds_read_b64_tr_b16 v[82:83], v207 offset:46592
	v_exp_f32_e32 v120, v120
	v_exp_f32_e32 v121, v121
	s_waitcnt lgkmcnt(4)
	v_mfma_f32_32x32x16_bf16 v[48:63], v[68:71], v[154:157], v[48:63]
	ds_read_b64_tr_b16 v[84:85], v207 offset:34816
	ds_read_b64_tr_b16 v[86:87], v207 offset:35328
	ds_read_b128 v[68:71], v204 offset:16384
	v_exp_f32_e32 v122, v122
	v_exp_f32_e32 v123, v123
	v_mfma_f32_32x32x16_bf16 v[32:47], v[72:75], v[154:157], v[32:47]
	ds_read_b64_tr_b16 v[72:73], v207 offset:38912
	ds_read_b64_tr_b16 v[74:75], v207 offset:39424
	ds_read_b128 v[64:67], v204 offset:20480
	v_exp_f32_e32 v124, v124
	v_exp_f32_e32 v125, v125
	s_waitcnt lgkmcnt(6)
	v_mfma_f32_32x32x16_bf16 v[16:31], v[76:79], v[154:157], v[16:31]
	ds_read_b64_tr_b16 v[76:77], v207 offset:43008
	ds_read_b64_tr_b16 v[78:79], v207 offset:43520
	ds_read_b128 v[182:185], v128 offset:16384
	v_exp_f32_e32 v126, v126
	v_exp_f32_e32 v127, v127
	v_mfma_f32_32x32x16_bf16 v[0:15], v[80:83], v[154:157], v[0:15]
	ds_read_b64_tr_b16 v[80:81], v207 offset:47104
	ds_read_b64_tr_b16 v[82:83], v207 offset:47616
	ds_read_b128 v[178:181], v128 offset:20480
	v_exp_f32_e32 v96, v96
	v_exp_f32_e32 v97, v97
	s_waitcnt lgkmcnt(7)
	v_mfma_f32_32x32x16_bf16 v[48:63], v[84:87], v[150:153], v[48:63]
	ds_read_b64_tr_b16 v[84:85], v207 offset:35840
	ds_read_b64_tr_b16 v[86:87], v207 offset:36352
	ds_read_b128 v[174:177], v205 offset:16384
	v_exp_f32_e32 v98, v98
	v_exp_f32_e32 v99, v99
	v_mfma_f32_32x32x16_bf16 v[32:47], v[72:75], v[150:153], v[32:47]
	ds_read_b64_tr_b16 v[72:73], v207 offset:39936
	ds_read_b64_tr_b16 v[74:75], v207 offset:40448
	ds_read_b128 v[170:173], v205 offset:20480
	v_exp_f32_e32 v100, v100
	v_exp_f32_e32 v101, v101
	s_waitcnt lgkmcnt(7)
	v_mfma_f32_32x32x16_bf16 v[16:31], v[76:79], v[150:153], v[16:31]
	ds_read_b64_tr_b16 v[76:77], v207 offset:44032
	ds_read_b64_tr_b16 v[78:79], v207 offset:44544
	ds_read_b128 v[166:169], v206 offset:16384
	v_exp_f32_e32 v102, v102
	v_exp_f32_e32 v103, v103
	v_mfma_f32_32x32x16_bf16 v[0:15], v[80:83], v[150:153], v[0:15]
	ds_read_b64_tr_b16 v[80:81], v207 offset:48128
	ds_read_b64_tr_b16 v[82:83], v207 offset:48640
	ds_read_b128 v[162:165], v206 offset:20480
	v_exp_f32_e32 v104, v104
	v_exp_f32_e32 v105, v105
	s_waitcnt lgkmcnt(7)
	v_mfma_f32_32x32x16_bf16 v[48:63], v[84:87], v[146:149], v[48:63]
	s_add_i32 m0, s22, 0x4000
	s_addk_i32 m0, 0x400
	s_add_u32 s100, s100, 0x58000
	s_addc_u32 s101, s101, 0
	global_load_lds_dwordx4 v201, s[100:101]
	v_exp_f32_e32 v106, v106
	v_exp_f32_e32 v107, v107
	v_mfma_f32_32x32x16_bf16 v[32:47], v[72:75], v[146:149], v[32:47]
	v_exp_f32_e32 v108, v108
	v_exp_f32_e32 v109, v109
	s_waitcnt lgkmcnt(1)
	v_mfma_f32_32x32x16_bf16 v[16:31], v[76:79], v[146:149], v[16:31]
	v_exp_f32_e32 v110, v110
	v_exp_f32_e32 v111, v111
	v_mfma_f32_32x32x16_bf16 v[0:15], v[80:83], v[146:149], v[0:15]
	v_add_f32_e32 v186, v209, v92
	s_waitcnt vmcnt(4) lgkmcnt(0)
	s_barrier
	v_mfma_f32_32x32x16_bf16 v[80:95], v[68:71], v[130:133], 0
	v_add_f32_e32 v68, v114, v112
	v_add_f32_e32 v69, v115, v113
	v_cvt_pk_bf16_f32 v158, v112, v113
	v_cvt_pk_bf16_f32 v159, v114, v115
	v_add_f32_e32 v68, v116, v68
	v_add_f32_e32 v112, v117, v69
	v_add_f32_e32 v146, v118, v68
	v_cvt_pk_bf16_f32 v160, v116, v117
	v_mfma_f32_32x32x16_bf16 v[64:79], v[64:67], v[130:133], 0
	v_add_f32_e32 v116, v119, v112
	v_cvt_pk_bf16_f32 v161, v118, v119
	ds_read_b64_tr_b16 v[112:113], v207 offset:0
	ds_read_b64_tr_b16 v[114:115], v207 offset:512
	v_add_f32_e32 v117, v120, v146
	v_add_f32_e32 v116, v121, v116
	v_mfma_f32_32x32x16_bf16 v[80:95], v[182:185], v[134:137], v[80:95]
	v_add_f32_e32 v146, v122, v117
	v_add_f32_e32 v147, v123, v116
	v_cvt_pk_bf16_f32 v154, v120, v121
	v_cvt_pk_bf16_f32 v155, v122, v123
	ds_read_b64_tr_b16 v[116:117], v207 offset:4096
	ds_read_b64_tr_b16 v[118:119], v207 offset:4608
	v_add_f32_e32 v120, v124, v146
	v_add_f32_e32 v121, v125, v147
	v_mfma_f32_32x32x16_bf16 v[64:79], v[178:181], v[134:137], v[64:79]
	v_add_f32_e32 v146, v126, v120
	v_add_f32_e32 v147, v127, v121
	v_cvt_pk_bf16_f32 v156, v124, v125
	v_cvt_pk_bf16_f32 v157, v126, v127
	ds_read_b64_tr_b16 v[120:121], v207 offset:8192
	ds_read_b64_tr_b16 v[122:123], v207 offset:8704
	v_add_f32_e32 v124, v96, v146
	v_add_f32_e32 v125, v97, v147
	v_mfma_f32_32x32x16_bf16 v[80:95], v[174:177], v[138:141], v[80:95]
	v_add_f32_e32 v124, v98, v124
	v_add_f32_e32 v125, v99, v125
	v_cvt_pk_bf16_f32 v150, v96, v97
	v_cvt_pk_bf16_f32 v151, v98, v99
	ds_read_b64_tr_b16 v[96:97], v207 offset:12288
	ds_read_b64_tr_b16 v[98:99], v207 offset:12800
	v_add_f32_e32 v124, v100, v124
	v_add_f32_e32 v125, v101, v125
	v_mfma_f32_32x32x16_bf16 v[64:79], v[170:173], v[138:141], v[64:79]
	s_add_i32 s90, s33, 5
	s_min_u32 s90, s90, s19
	s_mul_i32 s90, s90, 0x160000
	s_add_i32 m0, s5, 0x4000
	s_add_u32 s100, s44, s90
	s_addc_u32 s101, s45, 0
	global_load_lds_dwordx4 v199, s[100:101]
	v_add_f32_e32 v124, v102, v124
	v_add_f32_e32 v125, v103, v125
	v_cvt_pk_bf16_f32 v152, v100, v101
	v_cvt_pk_bf16_f32 v153, v102, v103
	v_add_f32_e32 v100, v104, v124
	v_add_f32_e32 v101, v105, v125
	v_mfma_f32_32x32x16_bf16 v[80:95], v[166:169], v[142:145], v[80:95]
	s_add_i32 m0, s32, 0x4000
	s_nop 0
	global_load_lds_dwordx4 v199, s[100:101] offset:128
	v_add_f32_e32 v100, v106, v100
	v_add_f32_e32 v101, v107, v101
	v_cvt_pk_bf16_f32 v146, v104, v105
	v_cvt_pk_bf16_f32 v147, v106, v107
	v_add_f32_e32 v100, v108, v100
	v_add_f32_e32 v101, v109, v101
	v_mfma_f32_32x32x16_bf16 v[64:79], v[162:165], v[142:145], v[64:79]
	s_add_i32 s90, s33, 3
	s_min_u32 s90, s90, s19
	s_mul_i32 s90, s90, 0x160000
	s_add_i32 m0, s22, 0x8000
	s_add_u32 s100, s44, s90
	s_addc_u32 s101, s45, 0
	global_load_lds_dwordx4 v201, s[100:101]
	v_add_f32_e32 v100, v110, v100
	v_add_f32_e32 v101, v111, v101
	v_cvt_pk_bf16_f32 v148, v108, v109
	v_cvt_pk_bf16_f32 v149, v110, v111
	v_add_f32_e32 v100, v100, v101
	v_exp_f32_e32 v80, v80
	v_exp_f32_e32 v81, v81
	s_waitcnt lgkmcnt(4)
	v_mfma_f32_32x32x16_bf16 v[48:63], v[112:115], v[158:161], v[48:63]
	v_add_f32_e32 v209, v186, v100
	ds_read_b64_tr_b16 v[100:101], v207 offset:1024
	ds_read_b64_tr_b16 v[102:103], v207 offset:1536
	v_exp_f32_e32 v82, v82
	v_exp_f32_e32 v83, v83
	v_mfma_f32_32x32x16_bf16 v[32:47], v[116:119], v[158:161], v[32:47]
	ds_read_b64_tr_b16 v[104:105], v207 offset:5120
	ds_read_b64_tr_b16 v[106:107], v207 offset:5632
	v_exp_f32_e32 v84, v84
	v_exp_f32_e32 v85, v85
	s_waitcnt lgkmcnt(4)
	v_mfma_f32_32x32x16_bf16 v[16:31], v[120:123], v[158:161], v[16:31]
	ds_read_b64_tr_b16 v[108:109], v207 offset:9216
	ds_read_b64_tr_b16 v[110:111], v207 offset:9728
	v_exp_f32_e32 v86, v86
	v_exp_f32_e32 v87, v87
	v_mfma_f32_32x32x16_bf16 v[0:15], v[96:99], v[158:161], v[0:15]
	ds_read_b64_tr_b16 v[112:113], v207 offset:13312
	ds_read_b64_tr_b16 v[114:115], v207 offset:13824
	v_exp_f32_e32 v88, v88
	v_exp_f32_e32 v89, v89
	s_waitcnt lgkmcnt(4)
	v_mfma_f32_32x32x16_bf16 v[48:63], v[100:103], v[154:157], v[48:63]
	ds_read_b64_tr_b16 v[116:117], v207 offset:2048
	ds_read_b64_tr_b16 v[118:119], v207 offset:2560
	ds_read_b128 v[100:103], v204 offset:32768
	v_exp_f32_e32 v90, v90
	v_exp_f32_e32 v91, v91
	v_mfma_f32_32x32x16_bf16 v[32:47], v[104:107], v[154:157], v[32:47]
	ds_read_b64_tr_b16 v[104:105], v207 offset:6144
	ds_read_b64_tr_b16 v[106:107], v207 offset:6656
	ds_read_b128 v[96:99], v204 offset:36864
	v_exp_f32_e32 v92, v92
	v_exp_f32_e32 v93, v93
	s_waitcnt lgkmcnt(6)
	v_mfma_f32_32x32x16_bf16 v[16:31], v[108:111], v[154:157], v[16:31]
	ds_read_b64_tr_b16 v[108:109], v207 offset:10240
	ds_read_b64_tr_b16 v[110:111], v207 offset:10752
	ds_read_b128 v[182:185], v128 offset:32768
	v_exp_f32_e32 v94, v94
	v_exp_f32_e32 v95, v95
	v_mfma_f32_32x32x16_bf16 v[0:15], v[112:115], v[154:157], v[0:15]
	ds_read_b64_tr_b16 v[112:113], v207 offset:14336
	ds_read_b64_tr_b16 v[114:115], v207 offset:14848
	ds_read_b128 v[178:181], v128 offset:36864
	v_exp_f32_e32 v64, v64
	v_exp_f32_e32 v65, v65
	s_waitcnt lgkmcnt(7)
	v_mfma_f32_32x32x16_bf16 v[48:63], v[116:119], v[150:153], v[48:63]
	ds_read_b64_tr_b16 v[116:117], v207 offset:3072
	ds_read_b64_tr_b16 v[118:119], v207 offset:3584
	ds_read_b128 v[174:177], v205 offset:32768
	v_exp_f32_e32 v66, v66
	v_exp_f32_e32 v67, v67
	v_mfma_f32_32x32x16_bf16 v[32:47], v[104:107], v[150:153], v[32:47]
	ds_read_b64_tr_b16 v[104:105], v207 offset:7168
	ds_read_b64_tr_b16 v[106:107], v207 offset:7680
	ds_read_b128 v[170:173], v205 offset:36864
	v_exp_f32_e32 v68, v68
	v_exp_f32_e32 v69, v69
	s_waitcnt lgkmcnt(7)
	v_mfma_f32_32x32x16_bf16 v[16:31], v[108:111], v[150:153], v[16:31]
	ds_read_b64_tr_b16 v[108:109], v207 offset:11264
	ds_read_b64_tr_b16 v[110:111], v207 offset:11776
	ds_read_b128 v[166:169], v206 offset:32768
	v_exp_f32_e32 v70, v70
	v_exp_f32_e32 v71, v71
	v_mfma_f32_32x32x16_bf16 v[0:15], v[112:115], v[150:153], v[0:15]
	ds_read_b64_tr_b16 v[112:113], v207 offset:15360
	ds_read_b64_tr_b16 v[114:115], v207 offset:15872
	ds_read_b128 v[162:165], v206 offset:36864
	v_exp_f32_e32 v72, v72
	v_exp_f32_e32 v73, v73
	s_waitcnt lgkmcnt(7)
	v_mfma_f32_32x32x16_bf16 v[48:63], v[116:119], v[146:149], v[48:63]
	s_add_i32 m0, s22, 0x8000
	s_addk_i32 m0, 0x400
	s_add_u32 s100, s100, 0x58000
	s_addc_u32 s101, s101, 0
	global_load_lds_dwordx4 v201, s[100:101]
	v_exp_f32_e32 v74, v74
	v_exp_f32_e32 v75, v75
	v_mfma_f32_32x32x16_bf16 v[32:47], v[104:107], v[146:149], v[32:47]
	v_exp_f32_e32 v76, v76
	v_exp_f32_e32 v77, v77
	s_waitcnt lgkmcnt(1)
	v_mfma_f32_32x32x16_bf16 v[16:31], v[108:111], v[146:149], v[16:31]
	v_exp_f32_e32 v78, v78
	v_exp_f32_e32 v79, v79
	v_mfma_f32_32x32x16_bf16 v[0:15], v[112:115], v[146:149], v[0:15]
	s_cmp_ge_u32 s24, s4
	s_mov_b32 s33, s24
	s_cbranch_scc1 .Lattn_exit
	s_add_i32 s24, s33, 2
	s_waitcnt vmcnt(4) lgkmcnt(0)
	s_barrier
	v_mfma_f32_32x32x16_bf16 v[112:127], v[100:103], v[130:133], 0
	v_add_f32_e32 v100, v82, v80
	v_add_f32_e32 v101, v83, v81
	v_cvt_pk_bf16_f32 v158, v80, v81
	v_cvt_pk_bf16_f32 v159, v82, v83
	v_add_f32_e32 v80, v84, v100
	v_add_f32_e32 v81, v85, v101
	v_add_f32_e32 v146, v86, v80
	v_cvt_pk_bf16_f32 v160, v84, v85
	v_mfma_f32_32x32x16_bf16 v[96:111], v[96:99], v[130:133], 0
	v_add_f32_e32 v84, v87, v81
	v_cvt_pk_bf16_f32 v161, v86, v87
	ds_read_b64_tr_b16 v[80:81], v207 offset:16384
	ds_read_b64_tr_b16 v[82:83], v207 offset:16896
	v_add_f32_e32 v85, v88, v146
	v_add_f32_e32 v84, v89, v84
	v_mfma_f32_32x32x16_bf16 v[112:127], v[182:185], v[134:137], v[112:127]
	v_add_f32_e32 v146, v90, v85
	v_add_f32_e32 v147, v91, v84
	v_cvt_pk_bf16_f32 v154, v88, v89
	v_cvt_pk_bf16_f32 v155, v90, v91
	ds_read_b64_tr_b16 v[84:85], v207 offset:20480
	ds_read_b64_tr_b16 v[86:87], v207 offset:20992
	v_add_f32_e32 v88, v92, v146
	v_add_f32_e32 v89, v93, v147
	v_mfma_f32_32x32x16_bf16 v[96:111], v[178:181], v[134:137], v[96:111]
	v_add_f32_e32 v146, v94, v88
	v_add_f32_e32 v147, v95, v89
	v_cvt_pk_bf16_f32 v156, v92, v93
	v_cvt_pk_bf16_f32 v157, v94, v95
	ds_read_b64_tr_b16 v[88:89], v207 offset:24576
	ds_read_b64_tr_b16 v[90:91], v207 offset:25088
	v_add_f32_e32 v92, v64, v146
	v_add_f32_e32 v93, v65, v147
	v_mfma_f32_32x32x16_bf16 v[112:127], v[174:177], v[138:141], v[112:127]
	v_add_f32_e32 v92, v66, v92
	v_add_f32_e32 v93, v67, v93
	v_cvt_pk_bf16_f32 v150, v64, v65
	v_cvt_pk_bf16_f32 v151, v66, v67
	ds_read_b64_tr_b16 v[64:65], v207 offset:28672
	ds_read_b64_tr_b16 v[66:67], v207 offset:29184
	v_add_f32_e32 v92, v68, v92
	v_add_f32_e32 v93, v69, v93
	v_mfma_f32_32x32x16_bf16 v[96:111], v[170:173], v[138:141], v[96:111]
	s_add_i32 s90, s33, 4
	s_min_u32 s90, s90, s19
	s_mul_i32 s90, s90, 0x160000
	s_add_i32 m0, s5, 0x8000
	s_add_u32 s100, s44, s90
	s_addc_u32 s101, s45, 0
	global_load_lds_dwordx4 v199, s[100:101]
	v_add_f32_e32 v92, v70, v92
	v_add_f32_e32 v93, v71, v93
	v_cvt_pk_bf16_f32 v152, v68, v69
	v_cvt_pk_bf16_f32 v153, v70, v71
	v_add_f32_e32 v68, v72, v92
	v_add_f32_e32 v69, v73, v93
	v_mfma_f32_32x32x16_bf16 v[112:127], v[166:169], v[142:145], v[112:127]
	s_add_i32 m0, s32, 0x8000
	s_nop 0
	global_load_lds_dwordx4 v199, s[100:101] offset:128
	v_add_f32_e32 v68, v74, v68
	v_add_f32_e32 v69, v75, v69
	v_cvt_pk_bf16_f32 v146, v72, v73
	v_cvt_pk_bf16_f32 v147, v74, v75
	v_add_f32_e32 v68, v76, v68
	v_add_f32_e32 v69, v77, v69
	v_mfma_f32_32x32x16_bf16 v[96:111], v[162:165], v[142:145], v[96:111]
	s_min_u32 s90, s24, s19
	s_mul_i32 s90, s90, 0x160000
	s_add_i32 m0, s22, 0x0
	s_add_u32 s100, s44, s90
	s_addc_u32 s101, s45, 0
	global_load_lds_dwordx4 v201, s[100:101]
	v_add_f32_e32 v68, v78, v68
	v_add_f32_e32 v69, v79, v69
	v_cvt_pk_bf16_f32 v148, v76, v77
	v_cvt_pk_bf16_f32 v149, v78, v79
	s_nop 0
	v_exp_f32_e32 v112, v112
	v_exp_f32_e32 v113, v113
	s_waitcnt lgkmcnt(4)
	v_mfma_f32_32x32x16_bf16 v[48:63], v[80:83], v[158:161], v[48:63]
	v_add_f32_e32 v92, v68, v69
	ds_read_b64_tr_b16 v[68:69], v207 offset:17408
	ds_read_b64_tr_b16 v[70:71], v207 offset:17920
	v_exp_f32_e32 v114, v114
	v_exp_f32_e32 v115, v115
	v_mfma_f32_32x32x16_bf16 v[32:47], v[84:87], v[158:161], v[32:47]
	ds_read_b64_tr_b16 v[72:73], v207 offset:21504
	ds_read_b64_tr_b16 v[74:75], v207 offset:22016
	v_exp_f32_e32 v116, v116
	v_exp_f32_e32 v117, v117
	s_waitcnt lgkmcnt(4)
	v_mfma_f32_32x32x16_bf16 v[16:31], v[88:91], v[158:161], v[16:31]
	ds_read_b64_tr_b16 v[76:77], v207 offset:25600
	ds_read_b64_tr_b16 v[78:79], v207 offset:26112
	v_exp_f32_e32 v118, v118
	v_exp_f32_e32 v119, v119
	v_mfma_f32_32x32x16_bf16 v[0:15], v[64:67], v[158:161], v[0:15]
	ds_read_b64_tr_b16 v[80:81], v207 offset:29696
	ds_read_b64_tr_b16 v[82:83], v207 offset:30208
	v_exp_f32_e32 v120, v120
	v_exp_f32_e32 v121, v121
	s_waitcnt lgkmcnt(4)
	v_mfma_f32_32x32x16_bf16 v[48:63], v[68:71], v[154:157], v[48:63]
	ds_read_b64_tr_b16 v[84:85], v207 offset:18432
	ds_read_b64_tr_b16 v[86:87], v207 offset:18944
	ds_read_b128 v[68:71], v204
	v_exp_f32_e32 v122, v122
	v_exp_f32_e32 v123, v123
	v_mfma_f32_32x32x16_bf16 v[32:47], v[72:75], v[154:157], v[32:47]
	ds_read_b64_tr_b16 v[72:73], v207 offset:22528
	ds_read_b64_tr_b16 v[74:75], v207 offset:23040
	ds_read_b128 v[64:67], v204 offset:4096
	v_exp_f32_e32 v124, v124
	v_exp_f32_e32 v125, v125
	s_waitcnt lgkmcnt(6)
	v_mfma_f32_32x32x16_bf16 v[16:31], v[76:79], v[154:157], v[16:31]
	ds_read_b64_tr_b16 v[76:77], v207 offset:26624
	ds_read_b64_tr_b16 v[78:79], v207 offset:27136
	ds_read_b128 v[182:185], v128
	v_exp_f32_e32 v126, v126
	v_exp_f32_e32 v127, v127
	v_mfma_f32_32x32x16_bf16 v[0:15], v[80:83], v[154:157], v[0:15]
	ds_read_b64_tr_b16 v[80:81], v207 offset:30720
	ds_read_b64_tr_b16 v[82:83], v207 offset:31232
	ds_read_b128 v[178:181], v128 offset:4096
	v_exp_f32_e32 v96, v96
	v_exp_f32_e32 v97, v97
	s_waitcnt lgkmcnt(7)
	v_mfma_f32_32x32x16_bf16 v[48:63], v[84:87], v[150:153], v[48:63]
	ds_read_b64_tr_b16 v[84:85], v207 offset:19456
	ds_read_b64_tr_b16 v[86:87], v207 offset:19968
	ds_read_b128 v[174:177], v205
	v_exp_f32_e32 v98, v98
	v_exp_f32_e32 v99, v99
	v_mfma_f32_32x32x16_bf16 v[32:47], v[72:75], v[150:153], v[32:47]
	ds_read_b64_tr_b16 v[72:73], v207 offset:23552
	ds_read_b64_tr_b16 v[74:75], v207 offset:24064
	ds_read_b128 v[170:173], v205 offset:4096
	v_exp_f32_e32 v100, v100
	v_exp_f32_e32 v101, v101
	s_waitcnt lgkmcnt(7)
	v_mfma_f32_32x32x16_bf16 v[16:31], v[76:79], v[150:153], v[16:31]
	ds_read_b64_tr_b16 v[76:77], v207 offset:27648
	ds_read_b64_tr_b16 v[78:79], v207 offset:28160
	ds_read_b128 v[166:169], v206
	v_exp_f32_e32 v102, v102
	v_exp_f32_e32 v103, v103
	v_mfma_f32_32x32x16_bf16 v[0:15], v[80:83], v[150:153], v[0:15]
	ds_read_b64_tr_b16 v[80:81], v207 offset:31744
	ds_read_b64_tr_b16 v[82:83], v207 offset:32256
	ds_read_b128 v[162:165], v206 offset:4096
	v_exp_f32_e32 v104, v104
	v_exp_f32_e32 v105, v105
	s_waitcnt lgkmcnt(7)
	v_mfma_f32_32x32x16_bf16 v[48:63], v[84:87], v[146:149], v[48:63]
	s_add_i32 m0, s22, 0x0
	s_addk_i32 m0, 0x400
	s_add_u32 s100, s100, 0x58000
	s_addc_u32 s101, s101, 0
	global_load_lds_dwordx4 v201, s[100:101]
	v_exp_f32_e32 v106, v106
	v_exp_f32_e32 v107, v107
	v_mfma_f32_32x32x16_bf16 v[32:47], v[72:75], v[146:149], v[32:47]
	v_exp_f32_e32 v108, v108
	v_exp_f32_e32 v109, v109
	s_waitcnt lgkmcnt(1)
	v_mfma_f32_32x32x16_bf16 v[16:31], v[76:79], v[146:149], v[16:31]
	v_exp_f32_e32 v110, v110
	v_exp_f32_e32 v111, v111
	v_mfma_f32_32x32x16_bf16 v[0:15], v[80:83], v[146:149], v[0:15]
	v_add_f32_e32 v186, v209, v92
	s_waitcnt vmcnt(4) lgkmcnt(0)
	s_barrier
	v_mfma_f32_32x32x16_bf16 v[80:95], v[68:71], v[130:133], 0
	v_add_f32_e32 v68, v114, v112
	v_add_f32_e32 v69, v115, v113
	v_cvt_pk_bf16_f32 v158, v112, v113
	v_cvt_pk_bf16_f32 v159, v114, v115
	v_add_f32_e32 v68, v116, v68
	v_add_f32_e32 v112, v117, v69
	v_add_f32_e32 v146, v118, v68
	v_cvt_pk_bf16_f32 v160, v116, v117
	v_mfma_f32_32x32x16_bf16 v[64:79], v[64:67], v[130:133], 0
	v_add_f32_e32 v116, v119, v112
	v_cvt_pk_bf16_f32 v161, v118, v119
	ds_read_b64_tr_b16 v[112:113], v207 offset:32768
	ds_read_b64_tr_b16 v[114:115], v207 offset:33280
	v_add_f32_e32 v117, v120, v146
	v_add_f32_e32 v116, v121, v116
	v_mfma_f32_32x32x16_bf16 v[80:95], v[182:185], v[134:137], v[80:95]
	v_add_f32_e32 v146, v122, v117
	v_add_f32_e32 v147, v123, v116
	v_cvt_pk_bf16_f32 v154, v120, v121
	v_cvt_pk_bf16_f32 v155, v122, v123
	ds_read_b64_tr_b16 v[116:117], v207 offset:36864
	ds_read_b64_tr_b16 v[118:119], v207 offset:37376
	v_add_f32_e32 v120, v124, v146
	v_add_f32_e32 v121, v125, v147
	v_mfma_f32_32x32x16_bf16 v[64:79], v[178:181], v[134:137], v[64:79]
	v_add_f32_e32 v146, v126, v120
	v_add_f32_e32 v147, v127, v121
	v_cvt_pk_bf16_f32 v156, v124, v125
	v_cvt_pk_bf16_f32 v157, v126, v127
	ds_read_b64_tr_b16 v[120:121], v207 offset:40960
	ds_read_b64_tr_b16 v[122:123], v207 offset:41472
	v_add_f32_e32 v124, v96, v146
	v_add_f32_e32 v125, v97, v147
	v_mfma_f32_32x32x16_bf16 v[80:95], v[174:177], v[138:141], v[80:95]
	v_add_f32_e32 v124, v98, v124
	v_add_f32_e32 v125, v99, v125
	v_cvt_pk_bf16_f32 v150, v96, v97
	v_cvt_pk_bf16_f32 v151, v98, v99
	ds_read_b64_tr_b16 v[96:97], v207 offset:45056
	ds_read_b64_tr_b16 v[98:99], v207 offset:45568
	v_add_f32_e32 v124, v100, v124
	v_add_f32_e32 v125, v101, v125
	v_mfma_f32_32x32x16_bf16 v[64:79], v[170:173], v[138:141], v[64:79]
	s_add_i32 s90, s33, 5
	s_min_u32 s90, s90, s19
	s_mul_i32 s90, s90, 0x160000
	s_add_i32 m0, s5, 0x0
	s_add_u32 s100, s44, s90
	s_addc_u32 s101, s45, 0
	global_load_lds_dwordx4 v199, s[100:101]
	v_add_f32_e32 v124, v102, v124
	v_add_f32_e32 v125, v103, v125
	v_cvt_pk_bf16_f32 v152, v100, v101
	v_cvt_pk_bf16_f32 v153, v102, v103
	v_add_f32_e32 v100, v104, v124
	v_add_f32_e32 v101, v105, v125
	v_mfma_f32_32x32x16_bf16 v[80:95], v[166:169], v[142:145], v[80:95]
	s_add_i32 m0, s32, 0x0
	s_nop 0
	global_load_lds_dwordx4 v199, s[100:101] offset:128
	v_add_f32_e32 v100, v106, v100
	v_add_f32_e32 v101, v107, v101
	v_cvt_pk_bf16_f32 v146, v104, v105
	v_cvt_pk_bf16_f32 v147, v106, v107
	v_add_f32_e32 v100, v108, v100
	v_add_f32_e32 v101, v109, v101
	v_mfma_f32_32x32x16_bf16 v[64:79], v[162:165], v[142:145], v[64:79]
	s_add_i32 s90, s33, 3
	s_min_u32 s90, s90, s19
	s_mul_i32 s90, s90, 0x160000
	s_add_i32 m0, s22, 0x4000
	s_add_u32 s100, s44, s90
	s_addc_u32 s101, s45, 0
	global_load_lds_dwordx4 v201, s[100:101]
	v_add_f32_e32 v100, v110, v100
	v_add_f32_e32 v101, v111, v101
	v_cvt_pk_bf16_f32 v148, v108, v109
	v_cvt_pk_bf16_f32 v149, v110, v111
	v_add_f32_e32 v100, v100, v101
	v_exp_f32_e32 v80, v80
	v_exp_f32_e32 v81, v81
	s_waitcnt lgkmcnt(4)
	v_mfma_f32_32x32x16_bf16 v[48:63], v[112:115], v[158:161], v[48:63]
	v_add_f32_e32 v209, v186, v100
	ds_read_b64_tr_b16 v[100:101], v207 offset:33792
	ds_read_b64_tr_b16 v[102:103], v207 offset:34304
	v_exp_f32_e32 v82, v82
	v_exp_f32_e32 v83, v83
	v_mfma_f32_32x32x16_bf16 v[32:47], v[116:119], v[158:161], v[32:47]
	ds_read_b64_tr_b16 v[104:105], v207 offset:37888
	ds_read_b64_tr_b16 v[106:107], v207 offset:38400
	v_exp_f32_e32 v84, v84
	v_exp_f32_e32 v85, v85
	s_waitcnt lgkmcnt(4)
	v_mfma_f32_32x32x16_bf16 v[16:31], v[120:123], v[158:161], v[16:31]
	ds_read_b64_tr_b16 v[108:109], v207 offset:41984
	ds_read_b64_tr_b16 v[110:111], v207 offset:42496
	v_exp_f32_e32 v86, v86
	v_exp_f32_e32 v87, v87
	v_mfma_f32_32x32x16_bf16 v[0:15], v[96:99], v[158:161], v[0:15]
	ds_read_b64_tr_b16 v[112:113], v207 offset:46080
	ds_read_b64_tr_b16 v[114:115], v207 offset:46592
	v_exp_f32_e32 v88, v88
	v_exp_f32_e32 v89, v89
	s_waitcnt lgkmcnt(4)
	v_mfma_f32_32x32x16_bf16 v[48:63], v[100:103], v[154:157], v[48:63]
	ds_read_b64_tr_b16 v[116:117], v207 offset:34816
	ds_read_b64_tr_b16 v[118:119], v207 offset:35328
	ds_read_b128 v[100:103], v204 offset:16384
	v_exp_f32_e32 v90, v90
	v_exp_f32_e32 v91, v91
	v_mfma_f32_32x32x16_bf16 v[32:47], v[104:107], v[154:157], v[32:47]
	ds_read_b64_tr_b16 v[104:105], v207 offset:38912
	ds_read_b64_tr_b16 v[106:107], v207 offset:39424
	ds_read_b128 v[96:99], v204 offset:20480
	v_exp_f32_e32 v92, v92
	v_exp_f32_e32 v93, v93
	s_waitcnt lgkmcnt(6)
	v_mfma_f32_32x32x16_bf16 v[16:31], v[108:111], v[154:157], v[16:31]
	ds_read_b64_tr_b16 v[108:109], v207 offset:43008
	ds_read_b64_tr_b16 v[110:111], v207 offset:43520
	ds_read_b128 v[182:185], v128 offset:16384
	v_exp_f32_e32 v94, v94
	v_exp_f32_e32 v95, v95
	v_mfma_f32_32x32x16_bf16 v[0:15], v[112:115], v[154:157], v[0:15]
	ds_read_b64_tr_b16 v[112:113], v207 offset:47104
	ds_read_b64_tr_b16 v[114:115], v207 offset:47616
	ds_read_b128 v[178:181], v128 offset:20480
	v_exp_f32_e32 v64, v64
	v_exp_f32_e32 v65, v65
	s_waitcnt lgkmcnt(7)
	v_mfma_f32_32x32x16_bf16 v[48:63], v[116:119], v[150:153], v[48:63]
	ds_read_b64_tr_b16 v[116:117], v207 offset:35840
	ds_read_b64_tr_b16 v[118:119], v207 offset:36352
	ds_read_b128 v[174:177], v205 offset:16384
	v_exp_f32_e32 v66, v66
	v_exp_f32_e32 v67, v67
	v_mfma_f32_32x32x16_bf16 v[32:47], v[104:107], v[150:153], v[32:47]
	ds_read_b64_tr_b16 v[104:105], v207 offset:39936
	ds_read_b64_tr_b16 v[106:107], v207 offset:40448
	ds_read_b128 v[170:173], v205 offset:20480
	v_exp_f32_e32 v68, v68
	v_exp_f32_e32 v69, v69
	s_waitcnt lgkmcnt(7)
	v_mfma_f32_32x32x16_bf16 v[16:31], v[108:111], v[150:153], v[16:31]
	ds_read_b64_tr_b16 v[108:109], v207 offset:44032
	ds_read_b64_tr_b16 v[110:111], v207 offset:44544
	ds_read_b128 v[166:169], v206 offset:16384
	v_exp_f32_e32 v70, v70
	v_exp_f32_e32 v71, v71
	v_mfma_f32_32x32x16_bf16 v[0:15], v[112:115], v[150:153], v[0:15]
	ds_read_b64_tr_b16 v[112:113], v207 offset:48128
	ds_read_b64_tr_b16 v[114:115], v207 offset:48640
	ds_read_b128 v[162:165], v206 offset:20480
	v_exp_f32_e32 v72, v72
	v_exp_f32_e32 v73, v73
	s_waitcnt lgkmcnt(7)
	v_mfma_f32_32x32x16_bf16 v[48:63], v[116:119], v[146:149], v[48:63]
	s_add_i32 m0, s22, 0x4000
	s_addk_i32 m0, 0x400
	s_add_u32 s100, s100, 0x58000
	s_addc_u32 s101, s101, 0
	global_load_lds_dwordx4 v201, s[100:101]
	v_exp_f32_e32 v74, v74
	v_exp_f32_e32 v75, v75
	v_mfma_f32_32x32x16_bf16 v[32:47], v[104:107], v[146:149], v[32:47]
	v_exp_f32_e32 v76, v76
	v_exp_f32_e32 v77, v77
	s_waitcnt lgkmcnt(1)
	v_mfma_f32_32x32x16_bf16 v[16:31], v[108:111], v[146:149], v[16:31]
	v_exp_f32_e32 v78, v78
	v_exp_f32_e32 v79, v79
	v_mfma_f32_32x32x16_bf16 v[0:15], v[112:115], v[146:149], v[0:15]
	s_cmp_ge_u32 s24, s4
	s_mov_b32 s33, s24
	s_cbranch_scc1 .Lattn_exit
	s_add_i32 s24, s33, 2
	s_waitcnt vmcnt(4) lgkmcnt(0)
	s_barrier
	s_branch .Lattn_top
.Lattn_exit:
	s_waitcnt vmcnt(4) lgkmcnt(0)
	s_barrier
